# sync poll loops sleep 127 between polls (poll traffic was slowing blocks still computing)
# speedup vs baseline: 1.0276x; 1.0276x over previous
.Lgb1_loop:
	global_load_dword v4, v0, s[6:7] sc1
	s_add_u32 s13, s13, 1
	s_waitcnt vmcnt(0)
	v_readfirstlane_b32 s12, v4
	s_nop 3
	s_cmp_gt_u32 s13, 0x80000
	s_cbranch_scc1 .Lgb1_done
	s_cmp_ge_u32 s12, s11
	s_cbranch_scc1 .Lgb1_done
	s_sleep 127
	s_branch .Lgb1_loop

.Lgs6_poll:
	global_load_dword v2, v0, s[6:7] sc1
	s_add_u32 s10, s10, 1
	s_waitcnt vmcnt(0)
	v_readfirstlane_b32 s2, v2
	s_nop 3
	s_cmp_gt_u32 s10, 0x40000
	s_cbranch_scc1 .Lgs6_done
	s_cmp_ge_u32 s2, 8
	s_cbranch_scc1 .Lgs6_done
	s_sleep 127
	s_branch .Lgs6_poll
